# adds: MLA QK/PV LDS reads hoisted with counted waits and v_max3 row-max; SB V fragments fetched with 4 dwordx4 gathers + v_permlane32_swap instead of 8 dwordx2 gathers
# speedup vs baseline: 1.0150x; 1.0150x over previous
; __device__ __forceinline__ int otid() { int t = threadIdx.x; asm volatile("" : "+v"(t)); return t; }
; __device__ __forceinline__ void sb_load(SbFrags& F, const bf16_t* Pm, const bf16_t* VT, size_t tok0, int kv0, int h, int r32, int hi) {
;     const bf16_t* krow = Pm + (tok0 + kv0 + r32) * PW + PC_SBK + h * 64;
; #pragma unroll
;     for (int s = 0; s < 4; ++s) F.kf[s] = *(const bf16x8*)(krow + 16 * s + 8 * hi);
; #pragma unroll
;     for (int s = 0; s < 2; ++s) {
;         const bf16_t* v0p = VT + (size_t)(h * 64 + r32) * VTLD + tok0 + kv0 + 16 * s + 4 * hi; const bf16_t* v1p = v0p + (size_t)32 * VTLD;
;         F.v[4 * s + 0] = *(const s16x4*)v0p; F.v[4 * s + 1] = *(const s16x4*)(v0p + 8); F.v[4 * s + 2] = *(const s16x4*)v1p; F.v[4 * s + 3] = *(const s16x4*)(v1p + 8);
;     }
; template <bool DRY> __device__ __forceinline__ void sb_unit(int b, int h, int qi, bf16_t* Pm, const bf16_t* VT) {
;     const int lane = otid() & 63, r32 = lane & 31, hi = lane >> 5;
;     const size_t tok0 = (size_t)b * SEQ; const int q0 = qi * 32;
;     bf16_t* qrow = Pm + (tok0 + q0 + r32) * PW + PC_SBQ + h * 64;
;     bf16x8 qf[4];
; #pragma unroll
;     for (int s = 0; s < 4; ++s) qf[s] = *(const bf16x8*)(qrow + 16 * s + 8 * hi);
;     float R = 0.f; f32x16 o0 = {}, o1 = {};
;     SbFrags cur, nxt;
;     sb_load(cur, Pm, VT, tok0, qi * 32, h, r32, hi);
.LBB0_741:
	v_ashrrev_i32_e32 v4, 9, v3
	v_mov_b32_e32 v0, v234
	s_waitcnt vmcnt(0)
	v_and_b32_e32 v100, 63, v3
	v_ashrrev_i32_e32 v5, 31, v4
	v_and_b32_e32 v15, 31, v0
	v_bfe_u32 v16, v0, 5, 1
	v_lshlrev_b64 v[0:1], 11, v[4:5]
	v_lshlrev_b32_e32 v17, 5, v100
	v_or3_b32 v8, v15, v17, v0
	v_mov_b64_e32 v[6:7], s[42:43]
	v_and_b32_e32 v14, 0x1c0, v3
	v_mad_u64_u32 v[6:7], s[4:5], v8, s24, v[6:7]
	v_mad_i32_i24 v7, v1, s24, v7
	v_lshlrev_b32_e32 v8, 1, v14
	v_mov_b32_e32 v9, v2
	v_lshl_add_u64 v[84:85], v[6:7], 0, v[8:9]
	v_lshlrev_b32_e32 v10, 4, v16
	v_mov_b32_e32 v11, v2
	v_lshl_add_u64 v[12:13], v[84:85], 0, v[10:11]
	global_load_dwordx4 v[52:55], v[12:13], off offset:1280
	global_load_dwordx4 v[56:59], v[12:13], off offset:1312
	global_load_dwordx4 v[60:63], v[12:13], off offset:1344
	global_load_dwordx4 v[64:67], v[12:13], off offset:1376
	v_or_b32_e32 v12, v15, v14
	v_mul_u32_u24_e32 v12, 0x8200, v12
	v_lshlrev_b32_e32 v12, 1, v12
	v_mov_b32_e32 v13, v2
	v_lshl_add_u64 v[12:13], s[38:39], 0, v[12:13]
	v_lshlrev_b64 v[4:5], 12, v[4:5]
	v_lshlrev_b32_e32 v6, 4, v16
	v_mov_b32_e32 v7, v2
	v_lshl_add_u64 v[4:5], v[12:13], 0, v[4:5]
	v_lshlrev_b32_e32 v12, 6, v100
	v_mov_b32_e32 v13, v2
	v_lshl_add_u64 v[12:13], v[4:5], 0, v[12:13]
	v_lshl_add_u64 v[88:89], v[4:5], 0, v[6:7]
	v_xor_b32_e32 v4, 32, v238
	v_add_u32_e32 v5, 64, v239
	v_cmp_lt_i32_e32 vcc, v4, v5
	v_lshlrev_b32_e32 v86, 2, v16
	v_and_b32_e32 v98, 63, v87
	v_cndmask_b32_e32 v4, v238, v4, vcc
	v_lshlrev_b32_e32 v101, 2, v4
	v_or_b32_e32 v4, 1, v86
	v_cmp_lt_u32_e64 s[46:47], v4, v15
	v_or_b32_e32 v4, 2, v86
	v_cmp_lt_u32_e64 s[48:49], v4, v15
	v_or_b32_e32 v4, 3, v86
	v_cmp_lt_u32_e64 s[50:51], v4, v15
	v_or_b32_e32 v4, 8, v86
	v_cmp_lt_u32_e64 s[52:53], v4, v15
	v_or_b32_e32 v4, 9, v86
	v_cmp_lt_u32_e64 s[54:55], v4, v15
	v_or_b32_e32 v4, 10, v86
	v_cmp_lt_u32_e64 s[56:57], v4, v15
	v_or_b32_e32 v4, 11, v86
	v_cmp_lt_u32_e64 s[58:59], v4, v15
	v_or_b32_e32 v4, 16, v86
	v_cmp_lt_u32_e64 s[60:61], v4, v15
	v_or_b32_e32 v4, 17, v86
	v_cmp_lt_u32_e64 s[62:63], v4, v15
	v_or_b32_e32 v4, 18, v86
	v_cmp_lt_u32_e64 s[64:65], v4, v15
	v_or_b32_e32 v4, 19, v86
	v_cmp_lt_u32_e64 s[66:67], v4, v15
	v_or_b32_e32 v4, 24, v86
	v_cmp_lt_u32_e64 s[68:69], v4, v15
	v_or_b32_e32 v4, 25, v86
	v_cmp_lt_u32_e64 s[70:71], v4, v15
	v_or_b32_e32 v4, 26, v86
	v_cmp_lt_u32_e64 s[72:73], v4, v15
	v_or_b32_e32 v4, 27, v86
	v_or_b32_e32 v0, v0, v15
	v_cmp_lt_u32_e64 s[74:75], v4, v15
	v_lshl_add_u64 v[4:5], s[42:43], 0, v[8:9]
	v_mov_b32_e32 v102, 0
	v_lshlrev_b32_e32 v99, 5, v98
	v_or_b32_e32 v90, v0, v17
	v_mov_b32_e32 v91, v1
	v_lshl_add_u64 v[94:95], v[12:13], 0, v[6:7]
	s_mov_b32 s28, 0
	v_cmp_eq_u32_e64 s[12:13], 0, v16
	v_cmp_lt_u32_e64 s[44:45], v86, v15
	v_lshl_add_u64 v[92:93], v[4:5], 0, v[10:11]
	s_mov_b64 s[34:35], 0
	v_mov_b32_e32 v4, 0
	v_mov_b32_e32 v5, v102
	v_mov_b32_e32 v6, v102
	v_mov_b32_e32 v7, v102
	v_mov_b32_e32 v8, v102
	v_mov_b32_e32 v9, v102
	v_mov_b32_e32 v10, v102
	v_mov_b32_e32 v11, v102
	v_mov_b32_e32 v12, v102
	v_mov_b32_e32 v13, v102
	v_mov_b32_e32 v14, v102
	v_mov_b32_e32 v15, v102
	v_mov_b32_e32 v16, v102
	v_mov_b32_e32 v17, v102
	v_mov_b32_e32 v18, v102
	v_mov_b32_e32 v19, v102
	v_mov_b32_e32 v20, 0
	v_mov_b32_e32 v21, v102
	v_mov_b32_e32 v22, v102
	v_mov_b32_e32 v23, v102
	v_mov_b32_e32 v24, v102
	v_mov_b32_e32 v25, v102
	v_mov_b32_e32 v26, v102
	v_mov_b32_e32 v27, v102
	v_mov_b32_e32 v28, v102
	v_mov_b32_e32 v29, v102
	v_mov_b32_e32 v30, v102
	v_mov_b32_e32 v31, v102
	v_mov_b32_e32 v32, v102
	v_mov_b32_e32 v33, v102
	v_mov_b32_e32 v34, v102
	v_mov_b32_e32 v35, v102
	v_med3_i32 v36, v100, 0, 1
	v_lshlrev_b32_e32 v36, 5, v36
	s_mov_b32 s4, 0x208000
	v_sub_u32_e32 v40, v99, v36
	v_add_co_u32_e32 v36, vcc, s4, v94
	v_mov_b32_e32 v41, v2
	s_nop 0
	v_addc_co_u32_e32 v37, vcc, 0, v95, vcc
	global_load_dwordx4 v[156:159], v[36:37], off offset:32
	global_load_dwordx4 v[160:163], v[94:95], off offset:32
	global_load_dwordx4 v[164:167], v[36:37], off
	global_load_dwordx4 v[168:171], v[94:95], off
	v_mad_u64_u32 v[36:37], s[4:5], v90, s24, v[92:93]
	v_mov_b32_e32 v38, v37
	v_mad_u64_u32 v[38:39], s[4:5], v91, s24, v[38:39]
	v_mov_b32_e32 v37, v38
	global_load_dwordx4 v[152:155], v[36:37], off offset:2400
	global_load_dwordx4 v[148:151], v[36:37], off offset:2368
	global_load_dwordx4 v[144:147], v[36:37], off offset:2336
	s_nop 0
	global_load_dwordx4 v[140:143], v[36:37], off offset:2304
	v_lshl_add_u64 v[90:91], v[0:1], 0, v[40:41]
	v_lshl_add_u64 v[94:95], v[40:41], 1, v[88:89]
	v_add_u32_e32 v100, -1, v100
	v_subrev_u32_e32 v99, 32, v99
	s_waitcnt vmcnt(0)
	v_permlane32_swap_b32_e32 v168, v170
	v_permlane32_swap_b32_e32 v169, v171
	v_permlane32_swap_b32_e32 v160, v162
	v_permlane32_swap_b32_e32 v161, v163
	v_permlane32_swap_b32_e32 v164, v166
	v_permlane32_swap_b32_e32 v165, v167
	v_permlane32_swap_b32_e32 v156, v158
	v_permlane32_swap_b32_e32 v157, v159
	v_mov_b32_e32 v136, v140
	v_mov_b32_e32 v137, v141
	v_mov_b32_e32 v138, v142
	v_mov_b32_e32 v139, v143
	v_mov_b32_e32 v112, v144
	v_mov_b32_e32 v113, v145
	v_mov_b32_e32 v114, v146
	v_mov_b32_e32 v115, v147
	v_mov_b32_e32 v108, v148
	v_mov_b32_e32 v109, v149
	v_mov_b32_e32 v110, v150
	v_mov_b32_e32 v111, v151
	v_mov_b32_e32 v104, v152
	v_mov_b32_e32 v105, v153
	v_mov_b32_e32 v106, v154
	v_mov_b32_e32 v107, v155
	v_mov_b32_e32 v68, v156
	v_mov_b32_e32 v69, v157
	v_mov_b32_e32 v70, v158
	v_mov_b32_e32 v71, v159
	v_mov_b32_e32 v72, v160
	v_mov_b32_e32 v73, v161
	v_mov_b32_e32 v74, v162
	v_mov_b32_e32 v75, v163
	v_mov_b32_e32 v76, v164
	v_mov_b32_e32 v77, v165
	v_mov_b32_e32 v78, v166
	v_mov_b32_e32 v79, v167
	v_mov_b32_e32 v80, v168
	v_mov_b32_e32 v81, v169
	v_mov_b32_e32 v82, v170
	v_mov_b32_e32 v83, v171
; __device__ __forceinline__ int crow(int r, int hi) { return (r & 3) + 8 * (r >> 2) + 4 * hi; }
; __device__ __forceinline__ void sb_load(SbFrags& F, const bf16_t* Pm, const bf16_t* VT, size_t tok0, int kv0, int h, int r32, int hi) {
;     const bf16_t* krow = Pm + (tok0 + kv0 + r32) * PW + PC_SBK + h * 64;
; #pragma unroll
;     for (int s = 0; s < 4; ++s) F.kf[s] = *(const bf16x8*)(krow + 16 * s + 8 * hi);
; #pragma unroll
;     for (int s = 0; s < 2; ++s) {
;         const bf16_t* v0p = VT + (size_t)(h * 64 + r32) * VTLD + tok0 + kv0 + 16 * s + 4 * hi; const bf16_t* v1p = v0p + (size_t)32 * VTLD;
;         F.v[4 * s + 0] = *(const s16x4*)v0p; F.v[4 * s + 1] = *(const s16x4*)(v0p + 8); F.v[4 * s + 2] = *(const s16x4*)v1p; F.v[4 * s + 3] = *(const s16x4*)(v1p + 8);
;     }
; template <bool DRY> __device__ __forceinline__ void sb_unit(int b, int h, int qi, bf16_t* Pm, const bf16_t* VT) {
;     ...
;         sb_load(nxt, Pm, VT, tok0, (kt > 0 ? kt - 1 : 0) * 32, h, r32, hi);
;         f32x16 p = {};
; #pragma unroll
;         for (int s = 0; s < 4; ++s) p = __builtin_amdgcn_mfma_f32_32x32x16_bf16(cur.kf[s], qf[s], p, 0, 0, 0);
;         const bool diag = (kt == qi);
;         float lk[16], inner[16], Tg[4], TP[4], pre[4];
; #pragma unroll
;         for (int r = 0; r < 16; ++r) {
;             const float z = p[r] * 0.125f; p[r] = z;
;             const float e = __expf(-fabsf(z)); const float sp = fmaxf(z, 0.f) + __logf(1.f + e);
;             const bool valid = !diag || (crow(r, hi) < r32);
;             lk[r] = valid ? -sp : 0.f;
.LBB0_742:
	v_med3_i32 v36, v100, 0, 1
	v_lshlrev_b32_e32 v36, 5, v36
	s_mov_b32 s4, 0x208000
	v_sub_u32_e32 v40, v99, v36
	v_add_co_u32_e32 v36, vcc, s4, v94
	v_mov_b32_e32 v41, v2
	s_nop 0
	v_addc_co_u32_e32 v37, vcc, 0, v95, vcc
	global_load_dwordx4 v[156:159], v[36:37], off offset:32
	global_load_dwordx4 v[160:163], v[94:95], off offset:32
	global_load_dwordx4 v[164:167], v[36:37], off
	global_load_dwordx4 v[168:171], v[94:95], off
	v_mad_u64_u32 v[36:37], s[4:5], v90, s24, v[92:93]
	v_mov_b32_e32 v38, v37
	v_mad_u64_u32 v[38:39], s[4:5], v91, s24, v[38:39]
	v_mov_b32_e32 v37, v38
	global_load_dwordx4 v[152:155], v[36:37], off offset:2400
	global_load_dwordx4 v[148:151], v[36:37], off offset:2368
	global_load_dwordx4 v[144:147], v[36:37], off offset:2336
	s_nop 0
	global_load_dwordx4 v[140:143], v[36:37], off offset:2304
	v_lshl_add_u64 v[90:91], v[0:1], 0, v[40:41]
	v_lshl_add_u64 v[94:95], v[40:41], 1, v[88:89]
	s_cmp_lg_u32 s28, 0
	s_cselect_b64 s[22:23], -1, 0
	s_or_b64 s[76:77], s[44:45], s[22:23]
	s_or_b64 s[78:79], s[46:47], s[22:23]
	s_or_b64 s[80:81], s[48:49], s[22:23]
	s_or_b64 s[88:89], s[56:57], s[22:23]
	s_or_b64 s[94:95], s[62:63], s[22:23]
	s_or_b64 s[96:97], s[64:65], s[22:23]
	s_or_b64 s[84:85], s[52:53], s[22:23]
	s_or_b64 s[86:87], s[54:55], s[22:23]
	s_or_b64 s[92:93], s[60:61], s[22:23]
	s_or_b64 s[90:91], s[58:59], s[22:23]
	s_or_b64 s[82:83], s[50:51], s[22:23]
	v_add_u32_e32 v100, -1, v100
	v_subrev_u32_e32 v99, 32, v99
	s_waitcnt vmcnt(8)
	v_mfma_f32_32x32x16_bf16 v[36:51], v[136:139], v[52:55], 0
	v_mfma_f32_32x32x16_bf16 v[36:51], v[112:115], v[56:59], v[36:51]
	v_mfma_f32_32x32x16_bf16 v[36:51], v[108:111], v[60:63], v[36:51]
	v_mfma_f32_32x32x16_bf16 v[36:51], v[104:107], v[64:67], v[36:51]
	s_nop 11
	v_mul_f32_e32 v96, 0x3e000000, v36
	v_mul_f32_e64 v97, |v96|, s25
	v_exp_f32_e32 v97, v97
	v_max_f32_e32 v96, 0, v96
	v_add_f32_e32 v97, 1.0, v97
	v_log_f32_e32 v97, v97
	s_nop 0
	v_mul_f32_e32 v103, 0x3f317217, v97
	v_fma_f32 v103, v97, s19, -v103
	v_fmac_f32_e32 v103, 0x3377d1cf, v97
	v_fmac_f32_e32 v103, 0x3f317217, v97
	v_mov_b32_e32 v97, v103
	v_add_f32_e32 v96, v96, v97
	v_cndmask_b32_e64 v103, 0, -v96, s[76:77]
	v_mul_f32_e32 v96, 0x3e000000, v37
	v_mul_f32_e64 v97, |v96|, s25
	v_exp_f32_e32 v97, v97
	v_max_f32_e32 v96, 0, v96
	v_fmamk_f32 v36, v36, 0x3e000000, v103
	v_add_f32_e32 v97, 1.0, v97
	v_log_f32_e32 v97, v97
	s_nop 0
	v_mul_f32_e32 v104, 0x3f317217, v97
	v_fma_f32 v104, v97, s19, -v104
	v_fmac_f32_e32 v104, 0x3377d1cf, v97
	v_fmac_f32_e32 v104, 0x3f317217, v97
	v_mov_b32_e32 v97, v104
	v_add_f32_e32 v96, v96, v97
	v_cndmask_b32_e64 v108, 0, -v96, s[78:79]
	v_mul_f32_e32 v96, 0x3e000000, v38
	v_mul_f32_e64 v97, |v96|, s25
	v_exp_f32_e32 v97, v97
	v_max_f32_e32 v96, 0, v96
	v_add_f32_e32 v97, 1.0, v97
	v_log_f32_e32 v97, v97
	s_nop 0
	v_mul_f32_e32 v104, 0x3f317217, v97
	v_fma_f32 v104, v97, s19, -v104
	v_fmac_f32_e32 v104, 0x3377d1cf, v97
	v_fmac_f32_e32 v104, 0x3f317217, v97
	v_mov_b32_e32 v97, v104
	v_add_f32_e32 v96, v96, v97
	v_cndmask_b32_e64 v109, 0, -v96, s[80:81]
	v_mul_f32_e32 v96, 0x3e000000, v39
	v_mul_f32_e64 v39, |v96|, s25
	v_exp_f32_e32 v39, v39
	v_max_f32_e32 v97, 0, v96
	v_add_f32_e32 v39, 1.0, v39
	v_log_f32_e32 v39, v39
	s_nop 0
	v_mul_f32_e32 v104, 0x3f317217, v39
	v_fma_f32 v104, v39, s19, -v104
	v_fmac_f32_e32 v104, 0x3377d1cf, v39
	v_fmac_f32_e32 v104, 0x3f317217, v39
	v_mov_b32_e32 v39, v104
	v_add_f32_e32 v110, v97, v39
	v_mul_f32_e32 v39, 0x3e000000, v40
	v_mul_f32_e64 v97, |v39|, s25
	v_exp_f32_e32 v97, v97
	v_max_f32_e32 v39, 0, v39
	v_add_f32_e32 v97, 1.0, v97
	v_log_f32_e32 v97, v97
	s_nop 0
	v_mul_f32_e32 v104, 0x3f317217, v97
	v_fma_f32 v104, v97, s19, -v104
	v_fmac_f32_e32 v104, 0x3377d1cf, v97
	v_fmac_f32_e32 v104, 0x3f317217, v97
	v_mov_b32_e32 v97, v104
	v_add_f32_e32 v39, v39, v97
	v_mul_f32_e32 v97, 0x3e000000, v41
	v_mul_f32_e64 v104, |v97|, s25
	v_exp_f32_e32 v104, v104
	v_max_f32_e32 v97, 0, v97
	v_cndmask_b32_e64 v39, 0, -v39, s[84:85]
	v_add_f32_e32 v104, 1.0, v104
	v_log_f32_e32 v104, v104
	s_nop 0
	v_mul_f32_e32 v105, 0x3f317217, v104
	v_fma_f32 v105, v104, s19, -v105
	v_fmac_f32_e32 v105, 0x3377d1cf, v104
	v_fmac_f32_e32 v105, 0x3f317217, v104
	v_mov_b32_e32 v104, v105
	v_add_f32_e32 v97, v97, v104
	v_mul_f32_e32 v104, 0x3e000000, v42
	v_mul_f32_e64 v105, |v104|, s25
	v_exp_f32_e32 v105, v105
	v_max_f32_e32 v104, 0, v104
	v_cndmask_b32_e64 v97, 0, -v97, s[86:87]
	v_add_f32_e32 v105, 1.0, v105
	v_log_f32_e32 v105, v105
	s_nop 0
	v_mul_f32_e32 v106, 0x3f317217, v105
	v_fma_f32 v106, v105, s19, -v106
	v_fmac_f32_e32 v106, 0x3377d1cf, v105
	v_fmac_f32_e32 v106, 0x3f317217, v105
	v_mov_b32_e32 v105, v106
	v_add_f32_e32 v104, v104, v105
	v_cndmask_b32_e64 v111, 0, -v104, s[88:89]
	v_mul_f32_e32 v104, 0x3e000000, v43
	v_mul_f32_e64 v43, |v104|, s25
	v_exp_f32_e32 v43, v43
	v_max_f32_e32 v105, 0, v104
	v_add_f32_e32 v43, 1.0, v43
	v_log_f32_e32 v43, v43
	s_nop 0
	v_mul_f32_e32 v106, 0x3f317217, v43
	v_fma_f32 v106, v43, s19, -v106
	v_fmac_f32_e32 v106, 0x3377d1cf, v43
	v_fmac_f32_e32 v106, 0x3f317217, v43
	v_mov_b32_e32 v43, v106
	v_add_f32_e32 v43, v105, v43
	v_mul_f32_e32 v105, 0x3e000000, v44
	v_mul_f32_e64 v106, |v105|, s25
	v_exp_f32_e32 v106, v106
	v_max_f32_e32 v105, 0, v105
	v_add_f32_e32 v106, 1.0, v106
	v_log_f32_e32 v106, v106
	s_nop 0
	v_mul_f32_e32 v107, 0x3f317217, v106
	v_fma_f32 v107, v106, s19, -v107
	v_fmac_f32_e32 v107, 0x3377d1cf, v106
	v_fmac_f32_e32 v107, 0x3f317217, v106
	v_mov_b32_e32 v106, v107
	v_add_f32_e32 v105, v105, v106
	v_mul_f32_e32 v106, 0x3e000000, v45
	v_mul_f32_e64 v107, |v106|, s25
	v_exp_f32_e32 v107, v107
; __device__ __forceinline__ int crow(int r, int hi) { return (r & 3) + 8 * (r >> 2) + 4 * hi; }
; template <bool DRY> __device__ __forceinline__ void sb_unit(int b, int h, int qi, bf16_t* Pm, const bf16_t* VT) {
;     ...
;         for (int r = 0; r < 16; ++r) {
;             const float z = p[r] * 0.125f; p[r] = z;
;             const float e = __expf(-fabsf(z)); const float sp = fmaxf(z, 0.f) + __logf(1.f + e);
;             const bool valid = !diag || (crow(r, hi) < r32);
;             lk[r] = valid ? -sp : 0.f;
;         }
; #pragma unroll
;         for (int g = 0; g < 4; ++g) {
;             const float s3 = lk[4 * g + 3], s2 = s3 + lk[4 * g + 2], s1 = s2 + lk[4 * g + 1];
;             inner[4 * g + 3] = 0.f; inner[4 * g + 2] = s3; inner[4 * g + 1] = s2; inner[4 * g] = s1; Tg[g] = s1 + lk[4 * g];
;             TP[g] = __shfl_xor(Tg[g], 32);
;         }
;         float run = 0.f;
; #pragma unroll
;         for (int g = 3; g >= 0; --g) { pre[g] = run + (hi == 0 ? TP[g] : 0.f); run += Tg[g] + TP[g]; }
	v_max_f32_e32 v106, 0, v106
	v_cndmask_b32_e64 v105, 0, -v105, s[92:93]
	v_add_f32_e32 v107, 1.0, v107
	v_log_f32_e32 v107, v107
	s_nop 0
	v_mul_f32_e32 v112, 0x3f317217, v107
	v_fma_f32 v112, v107, s19, -v112
	v_fmac_f32_e32 v112, 0x3377d1cf, v107
	v_fmac_f32_e32 v112, 0x3f317217, v107
	v_mov_b32_e32 v107, v112
	v_add_f32_e32 v106, v106, v107
	v_cndmask_b32_e64 v112, 0, -v106, s[94:95]
	v_mul_f32_e32 v106, 0x3e000000, v46
	v_mul_f32_e64 v107, |v106|, s25
	v_exp_f32_e32 v107, v107
	v_max_f32_e32 v106, 0, v106
	v_add_f32_e32 v107, 1.0, v107
	v_log_f32_e32 v107, v107
	s_nop 0
	v_mul_f32_e32 v113, 0x3f317217, v107
	v_fma_f32 v113, v107, s19, -v113
	v_fmac_f32_e32 v113, 0x3377d1cf, v107
	v_fmac_f32_e32 v113, 0x3f317217, v107
	v_mov_b32_e32 v107, v113
	v_add_f32_e32 v106, v106, v107
	v_cndmask_b32_e64 v113, 0, -v106, s[96:97]
	v_mul_f32_e32 v106, 0x3e000000, v47
	v_mul_f32_e64 v47, |v106|, s25
	v_exp_f32_e32 v47, v47
	v_max_f32_e32 v107, 0, v106
	v_add_f32_e32 v47, 1.0, v47
	v_log_f32_e32 v47, v47
	s_nop 0
	v_mul_f32_e32 v114, 0x3f317217, v47
	v_fma_f32 v114, v47, s19, -v114
	v_fmac_f32_e32 v114, 0x3377d1cf, v47
	v_fmac_f32_e32 v114, 0x3f317217, v47
	v_mov_b32_e32 v47, v114
	v_add_f32_e32 v47, v107, v47
	v_mul_f32_e32 v107, 0x3e000000, v48
	v_mul_f32_e64 v114, |v107|, s25
	v_exp_f32_e32 v114, v114
	v_max_f32_e32 v107, 0, v107
	s_or_b64 s[4:5], s[66:67], s[22:23]
	v_add_f32_e32 v114, 1.0, v114
	v_log_f32_e32 v114, v114
	s_nop 0
	v_mul_f32_e32 v115, 0x3f317217, v114
	v_fma_f32 v115, v114, s19, -v115
	v_fmac_f32_e32 v115, 0x3377d1cf, v114
	v_fmac_f32_e32 v115, 0x3f317217, v114
	v_mov_b32_e32 v114, v115
	v_add_f32_e32 v107, v107, v114
	s_or_b64 s[6:7], s[68:69], s[22:23]
	v_cndmask_b32_e64 v114, 0, -v107, s[6:7]
	v_mul_f32_e32 v107, 0x3e000000, v49
	v_mul_f32_e64 v115, |v107|, s25
	v_exp_f32_e32 v115, v115
	v_max_f32_e32 v107, 0, v107
	v_add_f32_e32 v115, 1.0, v115
	v_log_f32_e32 v115, v115
	s_nop 0
	v_mul_f32_e32 v116, 0x3f317217, v115
	v_fma_f32 v116, v115, s19, -v116
	v_fmac_f32_e32 v116, 0x3377d1cf, v115
	v_fmac_f32_e32 v116, 0x3f317217, v115
	v_mov_b32_e32 v115, v116
	v_add_f32_e32 v107, v107, v115
	s_or_b64 s[8:9], s[70:71], s[22:23]
	v_cndmask_b32_e64 v115, 0, -v107, s[8:9]
	v_mul_f32_e32 v107, 0x3e000000, v50
	v_mul_f32_e64 v116, |v107|, s25
	v_exp_f32_e32 v116, v116
	v_max_f32_e32 v107, 0, v107
	v_add_f32_e32 v116, 1.0, v116
	v_log_f32_e32 v116, v116
	s_nop 0
	v_mul_f32_e32 v117, 0x3f317217, v116
	v_fma_f32 v117, v116, s19, -v117
	v_fmac_f32_e32 v117, 0x3377d1cf, v116
	v_fmac_f32_e32 v117, 0x3f317217, v116
	v_mov_b32_e32 v116, v117
	v_add_f32_e32 v107, v107, v116
	s_or_b64 s[10:11], s[72:73], s[22:23]
	v_cndmask_b32_e64 v116, 0, -v107, s[10:11]
	v_mul_f32_e32 v107, 0x3e000000, v51
	v_mul_f32_e64 v117, |v107|, s25
	v_exp_f32_e32 v117, v117
	v_max_f32_e32 v107, 0, v107
	v_add_f32_e32 v117, 1.0, v117
	v_log_f32_e32 v117, v117
	s_nop 0
	v_mul_f32_e32 v118, 0x3f317217, v117
	v_fma_f32 v118, v117, s19, -v118
	v_fmac_f32_e32 v118, 0x3377d1cf, v117
	v_fmac_f32_e32 v118, 0x3f317217, v117
	v_mov_b32_e32 v117, v118
	v_add_f32_e32 v107, v107, v117
	s_or_b64 vcc, s[74:75], s[22:23]
	v_cndmask_b32_e64 v117, 0, -v107, vcc
	v_add_f32_e32 v118, v117, v116
	v_add_f32_e32 v119, v115, v118
	v_add_f32_e32 v107, v114, v119
	ds_bpermute_b32 v120, v101, v107
	v_fmac_f32_e32 v114, 0x3e000000, v48
	v_fmac_f32_e32 v115, 0x3e000000, v49
	v_fmac_f32_e32 v116, 0x3e000000, v50
	s_waitcnt lgkmcnt(0)
	v_add_f32_e32 v121, 0, v120
	v_add_f32_e32 v107, v107, v120
	v_add_f32_e32 v120, v102, v36
	v_fmamk_f32 v36, v37, 0x3e000000, v108
	v_add_f32_e32 v122, v102, v36
	v_fmamk_f32 v36, v38, 0x3e000000, v109
	v_add_f32_e32 v123, v102, v36
	v_fmamk_f32 v36, v40, 0x3e000000, v39
	v_add_f32_e32 v124, v102, v36
	v_fmamk_f32 v36, v41, 0x3e000000, v97
	v_add_f32_e32 v125, v102, v36
	v_fmamk_f32 v36, v42, 0x3e000000, v111
	v_add_f32_e32 v126, v102, v36
	v_fmamk_f32 v36, v44, 0x3e000000, v105
	v_add_f32_e32 v127, v102, v36
	v_fmamk_f32 v36, v45, 0x3e000000, v112
	v_add_f32_e32 v128, v102, v36
	v_fmamk_f32 v36, v46, 0x3e000000, v113
	v_add_f32_e32 v46, v102, v36
	v_cndmask_b32_e64 v36, 0, -v47, s[4:5]
	v_add_f32_e32 v47, v36, v113
	v_add_f32_e32 v112, v112, v47
	v_add_f32_e32 v38, v105, v112
	ds_bpermute_b32 v40, v101, v38
	v_add_f32_e32 v107, 0, v107
	v_cndmask_b32_e64 v121, 0, v121, s[12:13]
	s_waitcnt lgkmcnt(0)
	v_add_f32_e32 v38, v38, v40
	v_add_f32_e32 v105, v38, v107
	v_cndmask_b32_e64 v38, 0, -v43, s[90:91]
	v_add_f32_e32 v111, v38, v111
	v_add_f32_e32 v113, v97, v111
	v_cndmask_b32_e64 v37, 0, v40, s[12:13]
	v_add_f32_e32 v40, v39, v113
	ds_bpermute_b32 v41, v101, v40
	s_waitcnt lgkmcnt(0)
	v_cndmask_b32_e64 v39, 0, v41, s[12:13]
	v_add_f32_e32 v42, v40, v41
	v_pk_add_f32 v[40:41], v[104:105], v[38:39]
	v_add_f32_e32 v97, v42, v105
	v_cndmask_b32_e64 v42, 0, -v110, s[82:83]
	v_add_f32_e32 v39, v102, v40
	v_add_f32_e32 v40, v42, v109
	v_add_f32_e32 v104, v108, v40
	v_add_f32_e32 v44, v103, v104
	ds_bpermute_b32 v45, v101, v44
	s_waitcnt lgkmcnt(0)
; __device__ __forceinline__ unsigned cvtpk(float lo, float hi) { f32x2_t v = {lo, hi}; bf16x2_t b = __builtin_convertvector(v, bf16x2_t); return __builtin_bit_cast(unsigned, b); }
; __device__ __forceinline__ int crow(int r, int hi) { return (r & 3) + 8 * (r >> 2) + 4 * hi; }
; template <bool DRY> __device__ __forceinline__ void sb_unit(int b, int h, int qi, bf16_t* Pm, const bf16_t* VT) {
;     ...
;         for (int r = 0; r < 16; ++r) {
;             const bool valid = !diag || (crow(r, hi) < r32);
;             const float ex = fminf(p[r] + lk[r] + R + pre[r >> 2] + inner[r], 0.f);
;             p[r] = valid ? __expf(ex) : 0.f;
;         }
;         R += run;
; #pragma unroll
;         for (int s = 0; s < 2; ++s) {
;             const u32x4 pw = (u32x4){cvtpk(p[8 * s + 0], p[8 * s + 1]), cvtpk(p[8 * s + 2], p[8 * s + 3]), cvtpk(p[8 * s + 4], p[8 * s + 5]), cvtpk(p[8 * s + 6], p[8 * s + 7])};
;             const bf16x8 pf = __builtin_bit_cast(bf16x8, pw);
;             const s16x4 l0 = cur.v[4 * s], h0 = cur.v[4 * s + 1], l1 = cur.v[4 * s + 2], h1 = cur.v[4 * s + 3];
;             const bf16x8 v0 = (bf16x8){l0[0], l0[1], l0[2], l0[3], h0[0], h0[1], h0[2], h0[3]};
;             const bf16x8 v1 = (bf16x8){l1[0], l1[1], l1[2], l1[3], h1[0], h1[1], h1[2], h1[3]};
;             o0 = __builtin_amdgcn_mfma_f32_32x32x16_bf16(v0, pf, o0, 0, 0, 0);
;             o1 = __builtin_amdgcn_mfma_f32_32x32x16_bf16(v1, pf, o1, 0, 0, 0);
;         }
;         if (__all(R < -104.f)) break;
;         cur = nxt;
;     }
; #pragma unroll
;     for (int g = 0; g < 4; ++g) {
;         u32x2 w0, w1;
;         w0.x = cvtpk(o0[4 * g], o0[4 * g + 1]); w0.y = cvtpk(o0[4 * g + 2], o0[4 * g + 3]);
;         w1.x = cvtpk(o1[4 * g], o1[4 * g + 1]); w1.y = cvtpk(o1[4 * g + 2], o1[4 * g + 3]);
;         if (!DRY || R == 1234.56789f) { *(u32x2*)(qrow + 8 * g + 4 * hi) = w0; *(u32x2*)(qrow + 32 + 8 * g + 4 * hi) = w1; }
;     }
	v_cndmask_b32_e64 v43, 0, v45, s[12:13]
	v_add_f32_e32 v103, v44, v45
	v_pk_add_f32 v[44:45], v[96:97], v[42:43]
	v_add_f32_e32 v97, v103, v97
	v_add_f32_e32 v43, v102, v44
	v_add_f32_e32 v44, v120, v45
	v_add_f32_e32 v44, v104, v44
	v_add_f32_e32 v104, v126, v41
	v_add_f32_e32 v38, v38, v104
	v_min_f32_e32 v38, 0, v38
	v_mul_f32_e32 v38, 0x3fb8aa3b, v38
	v_exp_f32_e32 v38, v38
	v_add_f32_e32 v96, v122, v45
	v_add_f32_e32 v40, v40, v96
	v_add_f32_e32 v96, v123, v45
	v_cndmask_b32_e64 v104, 0, v38, s[88:89]
	v_add_f32_e32 v38, v39, v41
	v_min_f32_e32 v38, 0, v38
	v_mul_f32_e32 v38, 0x3fb8aa3b, v38
	v_exp_f32_e32 v38, v38
	v_add_f32_e32 v42, v42, v96
	v_add_f32_e32 v43, v43, v45
	v_add_f32_e32 v45, v124, v41
	v_add_f32_e32 v96, v125, v41
	v_cndmask_b32_e64 v41, 0, v38, s[90:91]
	v_pk_add_f32 v[38:39], v[106:107], v[36:37]
	v_add_f32_e32 v45, v113, v45
	v_add_f32_e32 v37, v127, v39
	v_add_f32_e32 v37, v112, v37
	v_min_f32_e32 v37, 0, v37
	v_mul_f32_e32 v37, 0x3fb8aa3b, v37
	v_exp_f32_e32 v37, v37
	v_add_f32_e32 v96, v111, v96
	v_min_f32_e32 v44, 0, v44
	v_min_f32_e32 v40, 0, v40
	v_cndmask_b32_e64 v105, 0, v37, s[92:93]
	v_add_f32_e32 v37, v128, v39
	v_add_f32_e32 v37, v47, v37
	v_min_f32_e32 v37, 0, v37
	v_mul_f32_e32 v37, 0x3fb8aa3b, v37
	v_exp_f32_e32 v37, v37
	v_min_f32_e32 v42, 0, v42
	v_min_f32_e32 v43, 0, v43
	v_min_f32_e32 v45, 0, v45
	v_cndmask_b32_e64 v47, 0, v37, s[94:95]
	v_add_f32_e32 v37, v46, v39
	v_add_f32_e32 v36, v36, v37
	v_min_f32_e32 v36, 0, v36
	v_mul_f32_e32 v36, 0x3fb8aa3b, v36
	v_exp_f32_e32 v36, v36
	v_min_f32_e32 v96, 0, v96
	v_mul_f32_e32 v44, 0x3fb8aa3b, v44
	v_mul_f32_e32 v40, 0x3fb8aa3b, v40
	v_cndmask_b32_e64 v46, 0, v36, s[96:97]
	v_add_f32_e32 v36, v102, v38
	v_add_f32_e32 v36, v36, v39
	v_min_f32_e32 v36, 0, v36
	v_mul_f32_e32 v36, 0x3fb8aa3b, v36
	v_exp_f32_e32 v36, v36
	v_mul_f32_e32 v42, 0x3fb8aa3b, v42
	v_mul_f32_e32 v43, 0x3fb8aa3b, v43
	v_mul_f32_e32 v45, 0x3fb8aa3b, v45
	v_cndmask_b32_e64 v106, 0, v36, s[4:5]
	v_add_f32_e32 v36, v102, v114
	v_add_f32_e32 v36, v121, v36
	v_add_f32_e32 v36, v119, v36
	v_min_f32_e32 v36, 0, v36
	v_mul_f32_e32 v36, 0x3fb8aa3b, v36
	v_exp_f32_e32 v36, v36
	v_mul_f32_e32 v96, 0x3fb8aa3b, v96
	v_exp_f32_e32 v44, v44
	v_exp_f32_e32 v40, v40
	v_cndmask_b32_e64 v48, 0, v36, s[6:7]
	v_add_f32_e32 v36, v102, v115
	v_add_f32_e32 v36, v121, v36
	v_add_f32_e32 v36, v118, v36
	v_min_f32_e32 v36, 0, v36
	v_mul_f32_e32 v36, 0x3fb8aa3b, v36
	v_exp_f32_e32 v36, v36
	v_exp_f32_e32 v42, v42
	v_exp_f32_e32 v43, v43
	v_exp_f32_e32 v45, v45
	v_cndmask_b32_e64 v49, 0, v36, s[8:9]
	v_add_f32_e32 v36, v102, v116
	v_add_f32_e32 v36, v121, v36
	v_add_f32_e32 v36, v117, v36
	v_min_f32_e32 v36, 0, v36
	v_mul_f32_e32 v36, 0x3fb8aa3b, v36
	v_exp_f32_e32 v36, v36
	v_fmac_f32_e32 v117, 0x3e000000, v51
	v_exp_f32_e32 v96, v96
	v_cndmask_b32_e64 v44, 0, v44, s[76:77]
	v_cndmask_b32_e64 v50, 0, v36, s[10:11]
	v_add_f32_e32 v36, v102, v117
	v_add_f32_e32 v36, v121, v36
	v_min_f32_e32 v36, 0, v36
	v_mul_f32_e32 v36, 0x3fb8aa3b, v36
	v_exp_f32_e32 v36, v36
	v_cndmask_b32_e64 v40, 0, v40, s[78:79]
	v_cndmask_b32_e64 v42, 0, v42, s[80:81]
	v_cndmask_b32_e64 v43, 0, v43, s[82:83]
	v_cndmask_b32_e64 v45, 0, v45, s[84:85]
	v_cndmask_b32_e64 v96, 0, v96, s[86:87]
	v_cndmask_b32_e32 v51, 0, v36, vcc
	v_cvt_pk_bf16_f32 v36, v44, v40
	v_cvt_pk_bf16_f32 v37, v42, v43
	v_cvt_pk_bf16_f32 v38, v45, v96
	v_cvt_pk_bf16_f32 v39, v104, v41
	v_add_f32_e32 v102, v102, v97
	s_mov_b32 s4, 0xc2d00000
	v_mfma_f32_32x32x16_bf16 v[4:19], v[80:83], v[36:39], v[4:19]
	v_cmp_gt_f32_e32 vcc, s4, v102
	s_cmp_eq_u64 vcc, exec
	s_cselect_b64 s[4:5], -1, 0
	v_cmp_eq_u32_e32 vcc, s28, v98
	s_or_b64 s[4:5], s[4:5], vcc
	s_add_i32 s28, s28, 1
	s_and_b64 s[4:5], exec, s[4:5]
	v_mfma_f32_32x32x16_bf16 v[20:35], v[76:79], v[36:39], v[20:35]
	v_cvt_pk_bf16_f32 v36, v105, v47
	v_cvt_pk_bf16_f32 v37, v46, v106
	v_cvt_pk_bf16_f32 v38, v48, v49
	v_cvt_pk_bf16_f32 v39, v50, v51
	s_or_b64 s[34:35], s[4:5], s[34:35]
	s_nop 0
	v_mfma_f32_32x32x16_bf16 v[4:19], v[72:75], v[36:39], v[4:19]
	v_mfma_f32_32x32x16_bf16 v[20:35], v[68:71], v[36:39], v[20:35]
	s_waitcnt vmcnt(0)
	v_permlane32_swap_b32_e32 v168, v170
	v_permlane32_swap_b32_e32 v169, v171
	v_permlane32_swap_b32_e32 v160, v162
	v_permlane32_swap_b32_e32 v161, v163
	v_permlane32_swap_b32_e32 v164, v166
	v_permlane32_swap_b32_e32 v165, v167
	v_permlane32_swap_b32_e32 v156, v158
	v_permlane32_swap_b32_e32 v157, v159
	v_mov_b32_e32 v136, v140
	v_mov_b32_e32 v137, v141
	v_mov_b32_e32 v138, v142
	v_mov_b32_e32 v139, v143
	v_mov_b32_e32 v112, v144
	v_mov_b32_e32 v113, v145
	v_mov_b32_e32 v114, v146
	v_mov_b32_e32 v115, v147
	v_mov_b32_e32 v108, v148
	v_mov_b32_e32 v109, v149
	v_mov_b32_e32 v110, v150
	v_mov_b32_e32 v111, v151
	v_mov_b32_e32 v104, v152
	v_mov_b32_e32 v105, v153
	v_mov_b32_e32 v106, v154
	v_mov_b32_e32 v107, v155
	v_mov_b32_e32 v68, v156
	v_mov_b32_e32 v69, v157
	v_mov_b32_e32 v70, v158
	v_mov_b32_e32 v71, v159
	v_mov_b32_e32 v72, v160
	v_mov_b32_e32 v73, v161
	v_mov_b32_e32 v74, v162
	v_mov_b32_e32 v75, v163
	v_mov_b32_e32 v76, v164
	v_mov_b32_e32 v77, v165
	v_mov_b32_e32 v78, v166
	v_mov_b32_e32 v79, v167
	v_mov_b32_e32 v80, v168
	v_mov_b32_e32 v81, v169
	v_mov_b32_e32 v82, v170
	v_mov_b32_e32 v83, v171
	s_andn2_b64 exec, exec, s[34:35]
	s_cbranch_execnz .LBB0_742
	s_or_b64 exec, exec, s[34:35]
	v_lshlrev_b32_e32 v0, 1, v86
	v_mov_b32_e32 v1, v2
	v_lshl_add_u64 v[0:1], v[84:85], 0, v[0:1]
	s_nop 4
	v_cvt_pk_bf16_f32 v4, v4, v5
	v_cvt_pk_bf16_f32 v5, v6, v7
	v_cvt_pk_bf16_f32 v6, v20, v21
	v_cvt_pk_bf16_f32 v7, v22, v23
	global_store_dwordx2 v[0:1], v[4:5], off offset:1280
	global_store_dwordx2 v[0:1], v[6:7], off offset:1344
	v_cvt_pk_bf16_f32 v4, v8, v9
	v_cvt_pk_bf16_f32 v5, v10, v11
	v_add_u32_e32 v3, s26, v3
	s_movk_i32 s4, 0x1fff
	v_cvt_pk_bf16_f32 v6, v24, v25
	v_cvt_pk_bf16_f32 v7, v26, v27
	global_store_dwordx2 v[0:1], v[4:5], off offset:1296
	global_store_dwordx2 v[0:1], v[6:7], off offset:1360
	v_cvt_pk_bf16_f32 v4, v12, v13
	v_cvt_pk_bf16_f32 v5, v14, v15
	v_cmp_lt_i32_e32 vcc, s4, v3
	v_cvt_pk_bf16_f32 v6, v28, v29
	v_cvt_pk_bf16_f32 v7, v30, v31
	global_store_dwordx2 v[0:1], v[4:5], off offset:1312
	global_store_dwordx2 v[0:1], v[6:7], off offset:1376
	v_cvt_pk_bf16_f32 v4, v16, v17
	v_cvt_pk_bf16_f32 v5, v18, v19
	s_or_b64 s[40:41], vcc, s[40:41]
	v_add_u16_e32 v87, s26, v87
	v_cvt_pk_bf16_f32 v6, v32, v33
	v_cvt_pk_bf16_f32 v7, v34, v35
	global_store_dwordx2 v[0:1], v[4:5], off offset:1328
	global_store_dwordx2 v[0:1], v[6:7], off offset:1392
	s_andn2_b64 exec, exec, s[40:41]
	s_cbranch_execnz .LBB0_741

; #define LAS __attribute__((address_space(3)))
; template <bool DRY> __device__ __forceinline__ void mla_unit(LAS unsigned char* lds, int b, int h, int qb, const bf16_t* Q, const bf16_t* Kn, const bf16_t* Pm, const bf16_t* VT, bf16_t* Y) {
;     ...
;         if (t <= tmax) {
;             f32x16 p0 = {}, p1 = {};
; #pragma unroll
;             for (int s = 0; s < 6; ++s) {
;                 const bf16x8 a0 = *(const LAS bf16x8*)(kbuf + r32 * MLA_KSTR + s * 32 + hi * 16);
;                 const bf16x8 a1 = *(const LAS bf16x8*)(kbuf + (32 + r32) * MLA_KSTR + s * 32 + hi * 16);
;                 p0 = __builtin_amdgcn_mfma_f32_32x32x16_bf16(a0, qf[s], p0, 0, 0, 0);
;                 p1 = __builtin_amdgcn_mfma_f32_32x32x16_bf16(a1, qf[s], p1, 0, 0, 0);
;             }
;             float mx = fmaxf(p0[0], p1[0]);
; #pragma unroll
;             for (int r = 1; r < 16; ++r) mx = fmaxf(mx, fmaxf(p0[r], p1[r]));
;             mx = fmaxf(mx, __shfl_xor(mx, 32));
;             const float cand = mx * C; const bool grow = cand > m_run + 8.f;
;             const float m_new = grow ? cand : m_run; const bool anyg = __any(grow);
;             const float alpha = anyg ? __builtin_amdgcn_exp2f(m_run - m_new) : 1.f; m_run = m_new;
;     ...
;                 const s16x4 l0 = *(const LAS s16x4*)(vbuf + r32 * MLA_VSTR + (16 * ks + 4 * hi) * 2);
;                 const s16x4 h0 = *(const LAS s16x4*)(vbuf + r32 * MLA_VSTR + (16 * ks + 8 + 4 * hi) * 2);
;                 const s16x4 l1 = *(const LAS s16x4*)(vbuf + (32 + r32) * MLA_VSTR + (16 * ks + 4 * hi) * 2);
;                 const s16x4 h1 = *(const LAS s16x4*)(vbuf + (32 + r32) * MLA_VSTR + (16 * ks + 8 + 4 * hi) * 2);
.LBB0_806:
	s_cmp_gt_i32 s57, s56
	s_cbranch_scc1 .LBB0_810
	v_add3_u32 v0, s58, v113, v108
	ds_read_b128 v[36:39], v0
	ds_read_b128 v[132:135], v0 offset:32
	ds_read_b128 v[52:55], v0 offset:6656
	ds_read_b128 v[136:139], v0 offset:6688
	ds_read_b128 v[140:143], v0 offset:64
	ds_read_b128 v[144:147], v0 offset:6720
	ds_read_b128 v[148:151], v0 offset:96
	ds_read_b128 v[152:155], v0 offset:6752
	ds_read_b128 v[156:159], v0 offset:128
	ds_read_b128 v[160:163], v0 offset:6784
	ds_read_b128 v[164:167], v0 offset:6816
	ds_read_b128 v[168:171], v0 offset:160
	s_waitcnt lgkmcnt(11)
	v_mfma_f32_32x32x16_bf16 v[36:51], v[36:39], v[84:87], 0
	s_waitcnt lgkmcnt(10)
	v_mfma_f32_32x32x16_bf16 v[36:51], v[132:135], v[68:71], v[36:51]
	s_waitcnt lgkmcnt(9)
	v_mfma_f32_32x32x16_bf16 v[52:67], v[52:55], v[84:87], 0
	s_waitcnt lgkmcnt(8)
	v_mfma_f32_32x32x16_bf16 v[52:67], v[136:139], v[68:71], v[52:67]
	s_waitcnt lgkmcnt(7)
	v_mfma_f32_32x32x16_bf16 v[36:51], v[140:143], v[72:75], v[36:51]
	s_waitcnt lgkmcnt(6)
	v_mfma_f32_32x32x16_bf16 v[52:67], v[144:147], v[72:75], v[52:67]
	s_waitcnt lgkmcnt(5)
	v_mfma_f32_32x32x16_bf16 v[36:51], v[148:151], v[76:79], v[36:51]
	s_waitcnt lgkmcnt(4)
	v_mfma_f32_32x32x16_bf16 v[52:67], v[152:155], v[76:79], v[52:67]
	s_waitcnt lgkmcnt(3)
	v_mfma_f32_32x32x16_bf16 v[36:51], v[156:159], v[80:83], v[36:51]
	s_waitcnt lgkmcnt(2)
	v_mfma_f32_32x32x16_bf16 v[52:67], v[160:163], v[80:83], v[52:67]
	s_waitcnt lgkmcnt(1)
	v_mfma_f32_32x32x16_bf16 v[52:67], v[164:167], v[92:95], v[52:67]
	s_waitcnt lgkmcnt(0)
	v_mfma_f32_32x32x16_bf16 v[36:51], v[168:171], v[92:95], v[36:51]
	v_add3_u32 v130, s23, v120, v106
	v_add_u32_e32 v129, 0x7800, v130
	v_add_u32_e32 v130, 0x6800, v130
	ds_read2_b64 v[172:175], v130 offset1:2
	ds_read2_b64 v[176:179], v129 offset0:64 offset1:66
	ds_read2_b64 v[180:183], v130 offset0:4 offset1:6
	ds_read2_b64 v[184:187], v129 offset0:68 offset1:70
	ds_read2_b64 v[188:191], v130 offset0:8 offset1:10
	ds_read2_b64 v[192:195], v129 offset0:72 offset1:74
	ds_read2_b64 v[196:199], v130 offset0:12 offset1:14
	ds_read2_b64 v[212:215], v129 offset0:76 offset1:78
	s_nop 1
	v_max3_f32 v0, v36, v52, v37
	v_max3_f32 v1, v53, v38, v54
	v_max3_f32 v0, v0, v39, v55
	v_max3_f32 v1, v1, v40, v56
	v_max3_f32 v0, v0, v41, v57
	v_max3_f32 v1, v1, v42, v58
	v_max3_f32 v0, v0, v43, v59
	v_max3_f32 v1, v1, v44, v60
	v_max3_f32 v0, v0, v45, v61
	v_max3_f32 v1, v1, v46, v62
	v_max3_f32 v0, v0, v47, v63
	v_max3_f32 v1, v1, v48, v64
	v_max3_f32 v0, v0, v49, v65
	v_max3_f32 v1, v1, v50, v66
	v_max3_f32 v0, v0, v51, v67
	v_max_f32_e32 v0, v0, v1
	v_xor_b32_e32 v1, 32, v238
	v_add_u32_e32 v3, 64, v239
	v_cmp_lt_i32_e32 vcc, v1, v3
	s_nop 1
	v_cndmask_b32_e32 v1, v238, v1, vcc
	v_lshlrev_b32_e32 v1, 2, v1
	ds_bpermute_b32 v1, v1, v0
	s_waitcnt lgkmcnt(0)
	v_max_f32_e32 v1, v1, v1
	v_max_f32_e32 v0, v0, v1
	v_mul_f32_e32 v0, 0x3e16c740, v0
	v_add_f32_e32 v1, 0x41000000, v122
	v_cmp_gt_f32_e32 vcc, v0, v1
	s_nop 1
	v_cndmask_b32_e32 v0, v122, v0, vcc
	s_cbranch_vccz .LBB0_809
	v_sub_f32_e32 v1, v122, v0
	v_exp_f32_e32 v122, v1
	s_nop 0
	v_pk_mul_f32 v[34:35], v[34:35], v[122:123] op_sel_hi:[1,0]
	v_pk_mul_f32 v[32:33], v[32:33], v[122:123] op_sel_hi:[1,0]
	v_pk_mul_f32 v[30:31], v[30:31], v[122:123] op_sel_hi:[1,0]
	v_pk_mul_f32 v[28:29], v[28:29], v[122:123] op_sel_hi:[1,0]
	v_pk_mul_f32 v[26:27], v[26:27], v[122:123] op_sel_hi:[1,0]
	v_pk_mul_f32 v[24:25], v[24:25], v[122:123] op_sel_hi:[1,0]
	v_pk_mul_f32 v[22:23], v[22:23], v[122:123] op_sel_hi:[1,0]
	v_pk_mul_f32 v[20:21], v[20:21], v[122:123] op_sel_hi:[1,0]
	v_pk_mul_f32 v[18:19], v[18:19], v[122:123] op_sel_hi:[1,0]
	v_pk_mul_f32 v[16:17], v[16:17], v[122:123] op_sel_hi:[1,0]
	v_pk_mul_f32 v[14:15], v[14:15], v[122:123] op_sel_hi:[1,0]
	v_pk_mul_f32 v[12:13], v[12:13], v[122:123] op_sel_hi:[1,0]
	v_pk_mul_f32 v[10:11], v[10:11], v[122:123] op_sel_hi:[1,0]
	v_pk_mul_f32 v[8:9], v[8:9], v[122:123] op_sel_hi:[1,0]
	v_pk_mul_f32 v[6:7], v[6:7], v[122:123] op_sel_hi:[1,0]
	v_pk_mul_f32 v[4:5], v[4:5], v[122:123] op_sel_hi:[1,0]
	v_mul_f32_e32 v121, v121, v122
; #define LAS __attribute__((address_space(3)))
; __device__ __forceinline__ unsigned cvtpk(float lo, float hi) { f32x2_t v = {lo, hi}; bf16x2_t b = __builtin_convertvector(v, bf16x2_t); return __builtin_bit_cast(unsigned, b); }
; template <bool DRY> __device__ __forceinline__ void mla_unit(LAS unsigned char* lds, int b, int h, int qb, const bf16_t* Q, const bf16_t* Kn, const bf16_t* Pm, const bf16_t* VT, bf16_t* Y) {
;     ...
;             float ls = 0.f;
; #pragma unroll
;             for (int r = 0; r < 16; ++r) { p0[r] = __builtin_amdgcn_exp2f(p0[r] * C - m_new); p1[r] = __builtin_amdgcn_exp2f(p1[r] * C - m_new); ls += p0[r] + p1[r]; }
;             if (anyg) { l_run *= alpha;
; #pragma unroll
;                 for (int r = 0; r < 16; ++r) { o0[r] *= alpha; o1[r] *= alpha; } }
;             l_run += ls;
;             u32x4 pw[4];
; #pragma unroll
;             for (int s = 0; s < 2; ++s) {
;                 pw[s] = (u32x4){cvtpk(p0[8 * s + 0], p0[8 * s + 1]), cvtpk(p0[8 * s + 2], p0[8 * s + 3]), cvtpk(p0[8 * s + 4], p0[8 * s + 5]), cvtpk(p0[8 * s + 6], p0[8 * s + 7])};
;                 pw[2 + s] = (u32x4){cvtpk(p1[8 * s + 0], p1[8 * s + 1]), cvtpk(p1[8 * s + 2], p1[8 * s + 3]), cvtpk(p1[8 * s + 4], p1[8 * s + 5]), cvtpk(p1[8 * s + 6], p1[8 * s + 7])};
;             }
; #pragma unroll
;             for (int ks = 0; ks < 4; ++ks) {
;                 const bf16x8 pf = __builtin_bit_cast(bf16x8, pw[ks]);
;                 const s16x4 l0 = *(const LAS s16x4*)(vbuf + r32 * MLA_VSTR + (16 * ks + 4 * hi) * 2);
;                 const s16x4 h0 = *(const LAS s16x4*)(vbuf + r32 * MLA_VSTR + (16 * ks + 8 + 4 * hi) * 2);
;                 const s16x4 l1 = *(const LAS s16x4*)(vbuf + (32 + r32) * MLA_VSTR + (16 * ks + 4 * hi) * 2);
;                 const s16x4 h1 = *(const LAS s16x4*)(vbuf + (32 + r32) * MLA_VSTR + (16 * ks + 8 + 4 * hi) * 2);
;                 const bf16x8 v0 = (bf16x8){l0[0], l0[1], l0[2], l0[3], h0[0], h0[1], h0[2], h0[3]};
;                 const bf16x8 v1 = (bf16x8){l1[0], l1[1], l1[2], l1[3], h1[0], h1[1], h1[2], h1[3]};
;                 o0 = __builtin_amdgcn_mfma_f32_32x32x16_bf16(v0, pf, o0, 0, 0, 0);
;                 o1 = __builtin_amdgcn_mfma_f32_32x32x16_bf16(v1, pf, o1, 0, 0, 0);
.LBB0_809:
	v_fma_f32 v1, v36, s1, -v0
	v_exp_f32_e32 v3, v1
	v_fma_f32 v1, v52, s1, -v0
	v_exp_f32_e32 v36, v1
	v_fma_f32 v37, v37, s1, -v0
	v_fma_f32 v52, v53, s1, -v0
	v_exp_f32_e32 v37, v37
	v_exp_f32_e32 v52, v52
	v_add_f32_e32 v1, v36, v3
	v_add_f32_e32 v1, 0, v1
	v_fma_f32 v38, v38, s1, -v0
	v_add_f32_e32 v53, v52, v37
	v_add_f32_e32 v1, v53, v1
	v_fma_f32 v53, v54, s1, -v0
	v_exp_f32_e32 v38, v38
	v_exp_f32_e32 v53, v53
	v_fma_f32 v39, v39, s1, -v0
	v_exp_f32_e32 v39, v39
	v_fma_f32 v40, v40, s1, -v0
	v_add_f32_e32 v54, v53, v38
	v_add_f32_e32 v1, v54, v1
	v_fma_f32 v54, v55, s1, -v0
	v_exp_f32_e32 v54, v54
	v_exp_f32_e32 v40, v40
	v_fma_f32 v41, v41, s1, -v0
	v_exp_f32_e32 v41, v41
	v_add_f32_e32 v55, v54, v39
	v_add_f32_e32 v1, v55, v1
	v_fma_f32 v55, v56, s1, -v0
	v_exp_f32_e32 v55, v55
	v_fma_f32 v42, v42, s1, -v0
	v_exp_f32_e32 v42, v42
	v_fma_f32 v43, v43, s1, -v0
	v_add_f32_e32 v56, v55, v40
	v_add_f32_e32 v1, v56, v1
	v_fma_f32 v56, v57, s1, -v0
	v_exp_f32_e32 v56, v56
	v_exp_f32_e32 v43, v43
	v_fma_f32 v44, v44, s1, -v0
	v_exp_f32_e32 v44, v44
	v_add_f32_e32 v57, v56, v41
	v_add_f32_e32 v1, v57, v1
	v_fma_f32 v57, v58, s1, -v0
	v_exp_f32_e32 v57, v57
	v_fma_f32 v45, v45, s1, -v0
	v_exp_f32_e32 v45, v45
	v_fma_f32 v46, v46, s1, -v0
	v_add_f32_e32 v58, v57, v42
	v_add_f32_e32 v1, v58, v1
	v_fma_f32 v58, v59, s1, -v0
	v_exp_f32_e32 v58, v58
	v_exp_f32_e32 v46, v46
	v_fma_f32 v47, v47, s1, -v0
	v_exp_f32_e32 v47, v47
	v_add_f32_e32 v59, v58, v43
	v_add_f32_e32 v1, v59, v1
	v_fma_f32 v59, v60, s1, -v0
	v_exp_f32_e32 v59, v59
	v_fma_f32 v48, v48, s1, -v0
	v_add_f32_e32 v60, v59, v44
	v_add_f32_e32 v1, v60, v1
	v_fma_f32 v60, v61, s1, -v0
	v_exp_f32_e32 v60, v60
	v_cvt_pk_bf16_f32 v44, v44, v45
	v_add_f32_e32 v61, v60, v45
	v_add_f32_e32 v1, v61, v1
	v_fma_f32 v61, v62, s1, -v0
	v_exp_f32_e32 v61, v61
	v_cvt_pk_bf16_f32 v45, v46, v47
	v_add_f32_e32 v62, v61, v46
	v_add_f32_e32 v1, v62, v1
	v_fma_f32 v62, v63, s1, -v0
	v_exp_f32_e32 v62, v62
	s_nop 0
	v_add_f32_e32 v63, v62, v47
	v_add_f32_e32 v1, v63, v1
	v_exp_f32_e32 v63, v48
	v_fma_f32 v48, v64, s1, -v0
	v_exp_f32_e32 v64, v48
	s_nop 0
	v_add_f32_e32 v48, v64, v63
	v_add_f32_e32 v1, v48, v1
	v_fma_f32 v48, v49, s1, -v0
	v_exp_f32_e32 v122, v48
	v_fma_f32 v48, v65, s1, -v0
	v_exp_f32_e32 v65, v48
	v_cvt_pk_bf16_f32 v49, v38, v39
	v_cvt_pk_bf16_f32 v46, v63, v122
	v_add_f32_e32 v48, v65, v122
	v_add_f32_e32 v1, v48, v1
	v_fma_f32 v48, v50, s1, -v0
	v_exp_f32_e32 v123, v48
	v_fma_f32 v48, v66, s1, -v0
	v_exp_f32_e32 v66, v48
	v_cvt_pk_bf16_f32 v38, v64, v65
	v_cvt_pk_bf16_f32 v50, v40, v41
	v_cvt_pk_bf16_f32 v40, v36, v52
	v_add_f32_e32 v48, v66, v123
	v_add_f32_e32 v1, v48, v1
	v_fma_f32 v48, v51, s1, -v0
	v_exp_f32_e32 v124, v48
	v_fma_f32 v48, v67, s1, -v0
	v_exp_f32_e32 v67, v48
	v_cvt_pk_bf16_f32 v51, v42, v43
	v_cvt_pk_bf16_f32 v41, v53, v54
	v_cvt_pk_bf16_f32 v42, v55, v56
	v_add_f32_e32 v48, v67, v124
	v_add_f32_e32 v1, v48, v1
	v_cvt_pk_bf16_f32 v48, v3, v37
	v_cvt_pk_bf16_f32 v43, v57, v58
	v_cvt_pk_bf16_f32 v36, v59, v60
	v_cvt_pk_bf16_f32 v37, v61, v62
	v_cvt_pk_bf16_f32 v47, v123, v124
	v_cvt_pk_bf16_f32 v39, v66, v67
	v_add_f32_e32 v121, v1, v121
	s_waitcnt lgkmcnt(0)
	v_mfma_f32_32x32x16_bf16 v[20:35], v[172:175], v[48:51], v[20:35]
	v_mfma_f32_32x32x16_bf16 v[4:19], v[176:179], v[48:51], v[4:19]
	v_mfma_f32_32x32x16_bf16 v[20:35], v[180:183], v[44:47], v[20:35]
	v_mfma_f32_32x32x16_bf16 v[4:19], v[184:187], v[44:47], v[4:19]
	v_mfma_f32_32x32x16_bf16 v[20:35], v[188:191], v[40:43], v[20:35]
	v_mfma_f32_32x32x16_bf16 v[4:19], v[192:195], v[40:43], v[4:19]
	v_mfma_f32_32x32x16_bf16 v[20:35], v[196:199], v[36:39], v[20:35]
	v_mfma_f32_32x32x16_bf16 v[4:19], v[212:215], v[36:39], v[4:19]
	s_branch .LBB0_811
